# GEMM K-loop: bookkeeping SALU/VALU between each MFMA cluster and its barrier moved behind the barrier
# speedup vs baseline: 1.0177x; 1.0045x over previous
; #define PG8_STAGE(bufoff, gbase, voff) do { _Pragma("unroll") for (int _i = 0; _i < 2; ++_i) \
;         __builtin_amdgcn_global_load_lds((const unsigned*)((const char*)(gbase) + (voff)[_i]), (LAS unsigned*)(lds + (bufoff) + ldsw + _i * 8192), 16, 0, 0); } while (0)
; #define PG8_LDA(dst, b, h) do { _Pragma("unroll") for (int m = 0; m < 4; ++m) _Pragma("unroll") for (int k = 0; k < 2; ++k) dst[m][k] = *(const LAS f16x8*)(lds + PG8_SA(b, h) + aoff + m * 2048 + k * 1024); } while (0)
; #define PG8_LDB(dst, b, h) do { _Pragma("unroll") for (int n = 0; n < 2; ++n) _Pragma("unroll") for (int k = 0; k < 2; ++k) dst[n][k] = *(const LAS f16x8*)(lds + PG8_SB(b, h) + boff + n * 2048 + k * 1024); } while (0)
; #define PG8_MMA(ai, bj, At, Bt) do { __builtin_amdgcn_s_setprio(1); _Pragma("unroll") for (int m = 0; m < 4; ++m) _Pragma("unroll") for (int n = 0; n < 2; ++n) _Pragma("unroll") for (int k = 0; k < 2; ++k) \
;         acc[ai][bj][m][n] = __builtin_amdgcn_mfma_f32_16x16x32_f16(Bt[n][k], At[m][k], acc[ai][bj][m][n], 0, 0, 0); __builtin_amdgcn_s_setprio(0); } while (0)
; #define PG8_WAIT_L(n) asm volatile("s_waitcnt lgkmcnt(" #n ")" ::: "memory")
; #define PG8_BAR __builtin_amdgcn_s_barrier()
; #define PG8_SCHED __builtin_amdgcn_sched_barrier(0)
; template <class Epi, class Sched>
; __device__ __forceinline__ void gemm_phase(LAS unsigned char* lds, const Gemm g, const Sched& S, const Epi& E) {
;     ...
;         for (int t = 0; t < nt; t += 2) {
;             const bool last = (t == nt - 2);
;             const char* a1 = cA + (size_t)(t + 1) * kstep;
;             const char* a2 = last ? nA : cA + (size_t)(t + 2) * kstep; const char* b2 = last ? nB : cB + (size_t)(t + 2) * kstep;
;             const char* a3 = a2 + kstep; const char* b3 = b2 + kstep;
;             if (last && has_next) S.a_ready(nxt);
;             PG8_LDB(B0, 0, 0); PG8_SCHED; PG8_LDA(At, 0, 0); PG8_STAGE(PG8_SA(1, 1), a1 + hstep, voffA);
;             PG8_WAIT_L(8); PG8_BAR; PG8_WAIT_L(0); PG8_MMA(0, 0, At, B0); PG8_BAR; PG8_SCHED;
;             PG8_LDB(B1, 0, 1); PG8_STAGE(PG8_SB(0, 0), b2, voffB);
;             PG8_BAR; PG8_WAIT_L(0); PG8_MMA(0, 1, At, B1); PG8_BAR;
;             PG8_LDA(At, 0, 1); PG8_STAGE(PG8_SA(0, 0), a2, voffA);
;             PG8_BAR; PG8_WAIT_L(0); PG8_MMA(1, 0, At, B0); PG8_BAR; PG8_SCHED;
.LBB0_829:
	s_add_i32 vcc_hi, s8, 2
	s_add_u32 s10, s6, 0x80
	s_addc_u32 s9, s7, 0
	s_add_i32 s17, 0, 0x10000
	s_cmp_eq_u32 s40, s8
	s_cselect_b32 s8, s66, s10
	s_cselect_b32 s9, s67, s9
	s_cselect_b32 s11, s69, vcc_lo
	s_cselect_b32 s10, s68, s41
	v_lshl_add_u64 v[156:157], s[6:7], 0, v[140:141]
	s_add_i32 m0, s82, 0xc000
	ds_read_b128 v[166:169], v161
	ds_read_b128 v[170:173], v161 offset:1024
	ds_read_b128 v[174:177], v161 offset:2048
	ds_read_b128 v[178:181], v161 offset:3072
	ds_read_b128 v[182:185], v161 offset:4096
	ds_read_b128 v[186:189], v161 offset:5120
	ds_read_b128 v[190:193], v161 offset:6144
	ds_read_b128 v[194:197], v161 offset:7168
	global_load_lds_dwordx4 v[156:157], off
	v_lshl_add_u64 v[156:157], s[6:7], 0, v[142:143]
	s_add_i32 m0, s82, 0xe000
	s_nop 0
	global_load_lds_dwordx4 v[156:157], off
	s_waitcnt lgkmcnt(8)
	s_barrier
	s_waitcnt lgkmcnt(0)
	s_setprio 1
	s_waitcnt lgkmcnt(0)
	v_mfma_f32_16x16x32_f16 v[126:129], v[144:147], v[166:169], v[126:129]
	v_mfma_f32_16x16x32_f16 v[122:125], v[152:155], v[166:169], v[122:125]
	v_mfma_f32_16x16x32_f16 v[110:113], v[144:147], v[174:177], v[110:113]
	v_mfma_f32_16x16x32_f16 v[106:109], v[152:155], v[174:177], v[106:109]
	v_mfma_f32_16x16x32_f16 v[94:97], v[144:147], v[182:185], v[94:97]
	v_mfma_f32_16x16x32_f16 v[90:93], v[152:155], v[182:185], v[90:93]
	v_mfma_f32_16x16x32_f16 v[78:81], v[144:147], v[190:193], v[78:81]
	v_mfma_f32_16x16x32_f16 v[74:77], v[152:155], v[190:193], v[74:77]
	v_mfma_f32_16x16x32_f16 v[126:129], v[148:151], v[170:173], v[126:129]
	v_mfma_f32_16x16x32_f16 v[122:125], v[162:165], v[170:173], v[122:125]
	v_mfma_f32_16x16x32_f16 v[110:113], v[148:151], v[178:181], v[110:113]
	v_mfma_f32_16x16x32_f16 v[106:109], v[162:165], v[178:181], v[106:109]
	v_mfma_f32_16x16x32_f16 v[94:97], v[148:151], v[186:189], v[94:97]
	v_mfma_f32_16x16x32_f16 v[90:93], v[162:165], v[186:189], v[90:93]
	v_mfma_f32_16x16x32_f16 v[78:81], v[148:151], v[194:197], v[78:81]
	v_mfma_f32_16x16x32_f16 v[74:77], v[162:165], v[194:197], v[74:77]
	s_setprio 0
	s_barrier
	s_add_i32 s86, 0, 0x14000
	s_add_i32 s17, s17, s71
	v_add_u32_e32 v16, s86, v159
	v_lshl_add_u64 v[156:157], s[10:11], 0, v[136:137]
	s_mov_b32 m0, s17
	ds_read_b128 v[198:201], v16
	ds_read_b128 v[230:233], v16 offset:1024
	ds_read_b128 v[234:237], v16 offset:2048
	ds_read_b128 v[238:241], v16 offset:3072
	global_load_lds_dwordx4 v[156:157], off
	v_lshl_add_u64 v[242:243], s[10:11], 0, v[132:133]
	s_add_i32 m0, s17, 0x2000
	s_nop 0
	global_load_lds_dwordx4 v[242:243], off
	s_barrier
	s_waitcnt lgkmcnt(0)
	s_setprio 1
	s_waitcnt lgkmcnt(0)
	v_mfma_f32_16x16x32_f16 v[118:121], v[198:201], v[166:169], v[118:121]
	v_mfma_f32_16x16x32_f16 v[114:117], v[234:237], v[166:169], v[114:117]
	v_mfma_f32_16x16x32_f16 v[102:105], v[198:201], v[174:177], v[102:105]
	v_mfma_f32_16x16x32_f16 v[98:101], v[234:237], v[174:177], v[98:101]
	v_mfma_f32_16x16x32_f16 v[86:89], v[198:201], v[182:185], v[86:89]
	v_mfma_f32_16x16x32_f16 v[82:85], v[234:237], v[182:185], v[82:85]
	v_mfma_f32_16x16x32_f16 v[70:73], v[198:201], v[190:193], v[70:73]
	v_mfma_f32_16x16x32_f16 v[66:69], v[234:237], v[190:193], v[66:69]
	v_mfma_f32_16x16x32_f16 v[118:121], v[230:233], v[170:173], v[118:121]
	v_mfma_f32_16x16x32_f16 v[114:117], v[238:241], v[170:173], v[114:117]
	v_mfma_f32_16x16x32_f16 v[102:105], v[230:233], v[178:181], v[102:105]
	v_mfma_f32_16x16x32_f16 v[98:101], v[238:241], v[178:181], v[98:101]
	v_mfma_f32_16x16x32_f16 v[86:89], v[230:233], v[186:189], v[86:89]
	v_mfma_f32_16x16x32_f16 v[82:85], v[238:241], v[186:189], v[82:85]
	v_mfma_f32_16x16x32_f16 v[70:73], v[230:233], v[194:197], v[70:73]
	v_mfma_f32_16x16x32_f16 v[66:69], v[238:241], v[194:197], v[66:69]
	s_setprio 0
	s_barrier
	s_mov_b32 m0, s82
	v_lshl_add_u64 v[244:245], s[8:9], 0, v[134:135]
	ds_read_b128 v[166:169], v161 offset:16384
	ds_read_b128 v[170:173], v161 offset:17408
	ds_read_b128 v[174:177], v161 offset:18432
	ds_read_b128 v[178:181], v161 offset:19456
	ds_read_b128 v[182:185], v161 offset:20480
	ds_read_b128 v[186:189], v161 offset:21504
	ds_read_b128 v[190:193], v161 offset:22528
	ds_read_b128 v[194:197], v161 offset:23552
	global_load_lds_dwordx4 v[244:245], off
	v_lshl_add_u64 v[246:247], s[8:9], 0, v[130:131]
	s_mov_b32 m0, s83
	s_nop 0
	global_load_lds_dwordx4 v[246:247], off
	s_waitcnt vmcnt(10)
	s_barrier
	s_waitcnt lgkmcnt(0)
	s_setprio 1
	s_waitcnt lgkmcnt(0)
	v_mfma_f32_16x16x32_f16 v[62:65], v[144:147], v[166:169], v[62:65]
	v_mfma_f32_16x16x32_f16 v[58:61], v[152:155], v[166:169], v[58:61]
	v_mfma_f32_16x16x32_f16 v[46:49], v[144:147], v[174:177], v[46:49]
	v_mfma_f32_16x16x32_f16 v[42:45], v[152:155], v[174:177], v[42:45]
	v_mfma_f32_16x16x32_f16 v[30:33], v[144:147], v[182:185], v[30:33]
	v_mfma_f32_16x16x32_f16 v[26:29], v[152:155], v[182:185], v[26:29]
	v_mfma_f32_16x16x32_f16 v[12:15], v[144:147], v[190:193], v[12:15]
	v_mfma_f32_16x16x32_f16 v[8:11], v[152:155], v[190:193], v[8:11]
	v_mfma_f32_16x16x32_f16 v[62:65], v[148:151], v[170:173], v[62:65]
	v_mfma_f32_16x16x32_f16 v[58:61], v[162:165], v[170:173], v[58:61]
	v_mfma_f32_16x16x32_f16 v[46:49], v[148:151], v[178:181], v[46:49]
	v_mfma_f32_16x16x32_f16 v[42:45], v[162:165], v[178:181], v[42:45]
	v_mfma_f32_16x16x32_f16 v[30:33], v[148:151], v[186:189], v[30:33]
	v_mfma_f32_16x16x32_f16 v[26:29], v[162:165], v[186:189], v[26:29]
	v_mfma_f32_16x16x32_f16 v[12:15], v[148:151], v[194:197], v[12:15]
	v_mfma_f32_16x16x32_f16 v[8:11], v[162:165], v[194:197], v[8:11]
	s_setprio 0
	s_barrier
; #define PG8_STAGE(bufoff, gbase, voff) do { _Pragma("unroll") for (int _i = 0; _i < 2; ++_i) \
;         __builtin_amdgcn_global_load_lds((const unsigned*)((const char*)(gbase) + (voff)[_i]), (LAS unsigned*)(lds + (bufoff) + ldsw + _i * 8192), 16, 0, 0); } while (0)
; #define PG8_LDA(dst, b, h) do { _Pragma("unroll") for (int m = 0; m < 4; ++m) _Pragma("unroll") for (int k = 0; k < 2; ++k) dst[m][k] = *(const LAS f16x8*)(lds + PG8_SA(b, h) + aoff + m * 2048 + k * 1024); } while (0)
; #define PG8_LDB(dst, b, h) do { _Pragma("unroll") for (int n = 0; n < 2; ++n) _Pragma("unroll") for (int k = 0; k < 2; ++k) dst[n][k] = *(const LAS f16x8*)(lds + PG8_SB(b, h) + boff + n * 2048 + k * 1024); } while (0)
; #define PG8_MMA(ai, bj, At, Bt) do { __builtin_amdgcn_s_setprio(1); _Pragma("unroll") for (int m = 0; m < 4; ++m) _Pragma("unroll") for (int n = 0; n < 2; ++n) _Pragma("unroll") for (int k = 0; k < 2; ++k) \
;         acc[ai][bj][m][n] = __builtin_amdgcn_mfma_f32_16x16x32_f16(Bt[n][k], At[m][k], acc[ai][bj][m][n], 0, 0, 0); __builtin_amdgcn_s_setprio(0); } while (0)
; #define PG8_WAIT_V(n) asm volatile("s_waitcnt vmcnt(" #n ")" ::: "memory")
; #define PG8_WAIT_L(n) asm volatile("s_waitcnt lgkmcnt(" #n ")" ::: "memory")
; #define PG8_BAR __builtin_amdgcn_s_barrier()
; #define PG8_SCHED __builtin_amdgcn_sched_barrier(0)
; template <class Epi, class Sched>
; __device__ __forceinline__ void gemm_phase(LAS unsigned char* lds, const Gemm g, const Sched& S, const Epi& E) {
;     ...
;             PG8_STAGE(PG8_SB(0, 1), b2 + hstep, voffB);
;             PG8_WAIT_V(6); PG8_BAR; PG8_MMA(1, 1, At, B1); PG8_BAR;
;             PG8_LDB(B0, 1, 0); PG8_SCHED; PG8_LDA(At, 1, 0); PG8_STAGE(PG8_SA(0, 1), a2 + hstep, voffA);
;             PG8_WAIT_L(8); PG8_BAR; PG8_WAIT_L(0); PG8_MMA(0, 0, At, B0); PG8_BAR; PG8_SCHED;
;             PG8_LDB(B1, 1, 1); PG8_STAGE(PG8_SB(1, 0), b3, voffB);
;             PG8_BAR; PG8_WAIT_L(0); PG8_MMA(0, 1, At, B1); PG8_BAR;
	v_add_u32_e32 v16, 0x18000, v159
	ds_read_b128 v[144:147], v16
	ds_read_b128 v[148:151], v16 offset:1024
	ds_read_b128 v[152:155], v16 offset:2048
	ds_read_b128 v[162:165], v16 offset:3072
	s_add_u32 s10, s10, s44
	s_addc_u32 s11, s11, 0
	s_add_i32 s17, s86, s71
	v_lshl_add_u64 v[248:249], s[10:11], 0, v[136:137]
	s_mov_b32 m0, s17
	v_lshl_add_u64 v[250:251], s[10:11], 0, v[132:133]
	global_load_lds_dwordx4 v[248:249], off
	s_add_i32 m0, s17, 0x2000
	s_nop 0
	global_load_lds_dwordx4 v[250:251], off
	s_waitcnt vmcnt(6)
	s_barrier
	s_setprio 1
	v_mfma_f32_16x16x32_f16 v[54:57], v[198:201], v[166:169], v[54:57]
	v_mfma_f32_16x16x32_f16 v[50:53], v[234:237], v[166:169], v[50:53]
	v_mfma_f32_16x16x32_f16 v[38:41], v[198:201], v[174:177], v[38:41]
	v_mfma_f32_16x16x32_f16 v[34:37], v[234:237], v[174:177], v[34:37]
	v_mfma_f32_16x16x32_f16 v[22:25], v[198:201], v[182:185], v[22:25]
	v_mfma_f32_16x16x32_f16 v[18:21], v[234:237], v[182:185], v[18:21]
	v_mfma_f32_16x16x32_f16 v[4:7], v[198:201], v[190:193], v[4:7]
	v_mfma_f32_16x16x32_f16 v[0:3], v[234:237], v[190:193], v[0:3]
	v_mfma_f32_16x16x32_f16 v[54:57], v[230:233], v[170:173], v[54:57]
	v_mfma_f32_16x16x32_f16 v[50:53], v[238:241], v[170:173], v[50:53]
	v_mfma_f32_16x16x32_f16 v[38:41], v[230:233], v[178:181], v[38:41]
	v_mfma_f32_16x16x32_f16 v[34:37], v[238:241], v[178:181], v[34:37]
	v_mfma_f32_16x16x32_f16 v[22:25], v[230:233], v[186:189], v[22:25]
	v_mfma_f32_16x16x32_f16 v[18:21], v[238:241], v[186:189], v[18:21]
	v_mfma_f32_16x16x32_f16 v[4:7], v[230:233], v[194:197], v[4:7]
	v_mfma_f32_16x16x32_f16 v[0:3], v[238:241], v[194:197], v[0:3]
	s_setprio 0
	s_barrier
	s_add_i32 s10, 0, 0x18000
	s_add_u32 s8, s8, s44
	s_addc_u32 s9, s9, 0
	s_mov_b32 m0, s84
	v_lshl_add_u64 v[198:199], s[8:9], 0, v[134:135]
	ds_read_b128 v[166:169], v161 offset:32768
	ds_read_b128 v[170:173], v161 offset:33792
	ds_read_b128 v[174:177], v161 offset:34816
	ds_read_b128 v[178:181], v161 offset:35840
	ds_read_b128 v[182:185], v161 offset:36864
	ds_read_b128 v[186:189], v161 offset:37888
	ds_read_b128 v[190:193], v161 offset:38912
	ds_read_b128 v[194:197], v161 offset:39936
	global_load_lds_dwordx4 v[198:199], off
	v_lshl_add_u64 v[198:199], s[8:9], 0, v[130:131]
	s_mov_b32 m0, s85
	s_nop 0
	global_load_lds_dwordx4 v[198:199], off
	s_waitcnt lgkmcnt(8)
	s_barrier
	s_waitcnt lgkmcnt(0)
	s_setprio 1
	s_waitcnt lgkmcnt(0)
	v_mfma_f32_16x16x32_f16 v[126:129], v[144:147], v[166:169], v[126:129]
	v_mfma_f32_16x16x32_f16 v[122:125], v[152:155], v[166:169], v[122:125]
	v_mfma_f32_16x16x32_f16 v[110:113], v[144:147], v[174:177], v[110:113]
	v_mfma_f32_16x16x32_f16 v[106:109], v[152:155], v[174:177], v[106:109]
	v_mfma_f32_16x16x32_f16 v[94:97], v[144:147], v[182:185], v[94:97]
	v_mfma_f32_16x16x32_f16 v[90:93], v[152:155], v[182:185], v[90:93]
	v_mfma_f32_16x16x32_f16 v[78:81], v[144:147], v[190:193], v[78:81]
	v_mfma_f32_16x16x32_f16 v[74:77], v[152:155], v[190:193], v[74:77]
	v_mfma_f32_16x16x32_f16 v[126:129], v[148:151], v[170:173], v[126:129]
	v_mfma_f32_16x16x32_f16 v[122:125], v[162:165], v[170:173], v[122:125]
	v_mfma_f32_16x16x32_f16 v[110:113], v[148:151], v[178:181], v[110:113]
	v_mfma_f32_16x16x32_f16 v[106:109], v[162:165], v[178:181], v[106:109]
	v_mfma_f32_16x16x32_f16 v[94:97], v[148:151], v[186:189], v[94:97]
	v_mfma_f32_16x16x32_f16 v[90:93], v[162:165], v[186:189], v[90:93]
	v_mfma_f32_16x16x32_f16 v[78:81], v[148:151], v[194:197], v[78:81]
	v_mfma_f32_16x16x32_f16 v[74:77], v[162:165], v[194:197], v[74:77]
	s_setprio 0
	s_barrier
	s_add_i32 s8, 0, 0x1c000
	s_add_i32 s9, s10, s71
	v_add_u32_e32 v16, s8, v159
	v_lshl_add_u64 v[156:157], v[156:157], 0, s[90:91]
	s_mov_b32 m0, s9
	ds_read_b128 v[198:201], v16
	ds_read_b128 v[230:233], v16 offset:1024
	ds_read_b128 v[234:237], v16 offset:2048
	ds_read_b128 v[238:241], v16 offset:3072
	global_load_lds_dwordx4 v[156:157], off
	v_lshl_add_u64 v[156:157], v[242:243], 0, s[90:91]
	s_add_i32 m0, s9, 0x2000
	s_nop 0
	global_load_lds_dwordx4 v[156:157], off
	s_barrier
	s_waitcnt lgkmcnt(0)
	s_setprio 1
	s_waitcnt lgkmcnt(0)
	v_mfma_f32_16x16x32_f16 v[118:121], v[198:201], v[166:169], v[118:121]
	v_mfma_f32_16x16x32_f16 v[114:117], v[234:237], v[166:169], v[114:117]
	v_mfma_f32_16x16x32_f16 v[102:105], v[198:201], v[174:177], v[102:105]
	v_mfma_f32_16x16x32_f16 v[98:101], v[234:237], v[174:177], v[98:101]
	v_mfma_f32_16x16x32_f16 v[86:89], v[198:201], v[182:185], v[86:89]
	v_mfma_f32_16x16x32_f16 v[82:85], v[234:237], v[182:185], v[82:85]
	v_mfma_f32_16x16x32_f16 v[70:73], v[198:201], v[190:193], v[70:73]
	v_mfma_f32_16x16x32_f16 v[66:69], v[234:237], v[190:193], v[66:69]
	v_mfma_f32_16x16x32_f16 v[118:121], v[230:233], v[170:173], v[118:121]
	v_mfma_f32_16x16x32_f16 v[114:117], v[238:241], v[170:173], v[114:117]
	v_mfma_f32_16x16x32_f16 v[102:105], v[230:233], v[178:181], v[102:105]
	v_mfma_f32_16x16x32_f16 v[98:101], v[238:241], v[178:181], v[98:101]
	v_mfma_f32_16x16x32_f16 v[86:89], v[230:233], v[186:189], v[86:89]
	v_mfma_f32_16x16x32_f16 v[82:85], v[238:241], v[186:189], v[82:85]
	v_mfma_f32_16x16x32_f16 v[70:73], v[230:233], v[194:197], v[70:73]
	v_mfma_f32_16x16x32_f16 v[66:69], v[238:241], v[194:197], v[66:69]
	s_setprio 0
	s_barrier
; #define PG8_STAGE(bufoff, gbase, voff) do { _Pragma("unroll") for (int _i = 0; _i < 2; ++_i) \
;         __builtin_amdgcn_global_load_lds((const unsigned*)((const char*)(gbase) + (voff)[_i]), (LAS unsigned*)(lds + (bufoff) + ldsw + _i * 8192), 16, 0, 0); } while (0)
; #define PG8_LDA(dst, b, h) do { _Pragma("unroll") for (int m = 0; m < 4; ++m) _Pragma("unroll") for (int k = 0; k < 2; ++k) dst[m][k] = *(const LAS f16x8*)(lds + PG8_SA(b, h) + aoff + m * 2048 + k * 1024); } while (0)
; #define PG8_MMA(ai, bj, At, Bt) do { __builtin_amdgcn_s_setprio(1); _Pragma("unroll") for (int m = 0; m < 4; ++m) _Pragma("unroll") for (int n = 0; n < 2; ++n) _Pragma("unroll") for (int k = 0; k < 2; ++k) \
;         acc[ai][bj][m][n] = __builtin_amdgcn_mfma_f32_16x16x32_f16(Bt[n][k], At[m][k], acc[ai][bj][m][n], 0, 0, 0); __builtin_amdgcn_s_setprio(0); } while (0)
;     __device__ __forceinline__ void operator()(const f32x4 (&acc)[2][2][4][2], const Unit& u, int wr, int wc, int fr, int fq) const {
;     ...
;             f16_t* O = (f16_t*)out;
;             const int row0 = u.pm * BM + wr * 64 + fr; const int col0 = u.pn * BM + wc * 32 + 8 * fq;
;             const float lo = mode == 1 ? 0.f : -3.0e38f;
; #pragma unroll
;             for (int ai = 0; ai < 2; ++ai)
; #pragma unroll
;                 for (int m = 0; m < 4; ++m) { f16_t* rowp = O + (size_t)(row0 + ai * HALF + m * 16) * ldc + col0;
; #pragma unroll
;                     for (int bj = 0; bj < 2; ++bj) { f32x4 v0 = acc[ai][bj][m][0], v1 = acc[ai][bj][m][1];
;                         if (mode == 1) {
; #pragma unroll
;                             for (int j = 0; j < 4; ++j) { float a = fmaxf(v0[j], lo), b = fmaxf(v1[j], lo); v0[j] = a * a; v1[j] = b * b; } }
;                         u32x4 w; w.x = pkh(v0[0], v0[1]); w.y = pkh(v0[2], v0[3]); w.z = pkh(v1[0], v1[1]); w.w = pkh(v1[2], v1[3]);
;                         *(u32x4*)(rowp + bj * HALF) = w; } }
; template <class Epi, class Sched>
; __device__ __forceinline__ void gemm_phase(LAS unsigned char* lds, const Gemm g, const Sched& S, const Epi& E) {
;     ...
;             PG8_LDA(At, 1, 1); PG8_STAGE(PG8_SA(1, 0), a3, voffA);
;             PG8_BAR; PG8_WAIT_L(0); PG8_MMA(1, 0, At, B0); PG8_BAR; PG8_SCHED;
;             PG8_STAGE(PG8_SB(1, 1), b3 + hstep, voffB);
;             PG8_WAIT_V(6); PG8_BAR; PG8_MMA(1, 1, At, B1); PG8_BAR;
;         }
	s_mov_b32 m0, s94
	v_lshl_add_u64 v[156:157], v[244:245], 0, s[90:91]
	ds_read_b128 v[166:169], v161 offset:49152
	ds_read_b128 v[170:173], v161 offset:50176
	ds_read_b128 v[174:177], v161 offset:51200
	ds_read_b128 v[178:181], v161 offset:52224
	ds_read_b128 v[182:185], v161 offset:53248
	ds_read_b128 v[186:189], v161 offset:54272
	ds_read_b128 v[190:193], v161 offset:55296
	ds_read_b128 v[194:197], v161 offset:56320
	global_load_lds_dwordx4 v[156:157], off
	v_lshl_add_u64 v[156:157], v[246:247], 0, s[90:91]
	s_mov_b32 m0, s95
	s_nop 0
	global_load_lds_dwordx4 v[156:157], off
	s_waitcnt vmcnt(10)
	s_barrier
	s_waitcnt lgkmcnt(0)
	s_setprio 1
	s_waitcnt lgkmcnt(0)
	v_mfma_f32_16x16x32_f16 v[62:65], v[144:147], v[166:169], v[62:65]
	v_mfma_f32_16x16x32_f16 v[58:61], v[152:155], v[166:169], v[58:61]
	v_mfma_f32_16x16x32_f16 v[46:49], v[144:147], v[174:177], v[46:49]
	v_mfma_f32_16x16x32_f16 v[42:45], v[152:155], v[174:177], v[42:45]
	v_mfma_f32_16x16x32_f16 v[30:33], v[144:147], v[182:185], v[30:33]
	v_mfma_f32_16x16x32_f16 v[26:29], v[152:155], v[182:185], v[26:29]
	v_mfma_f32_16x16x32_f16 v[12:15], v[144:147], v[190:193], v[12:15]
	v_mfma_f32_16x16x32_f16 v[8:11], v[152:155], v[190:193], v[8:11]
	v_mfma_f32_16x16x32_f16 v[62:65], v[148:151], v[170:173], v[62:65]
	v_mfma_f32_16x16x32_f16 v[58:61], v[162:165], v[170:173], v[58:61]
	v_mfma_f32_16x16x32_f16 v[46:49], v[148:151], v[178:181], v[46:49]
	v_mfma_f32_16x16x32_f16 v[42:45], v[162:165], v[178:181], v[42:45]
	v_mfma_f32_16x16x32_f16 v[30:33], v[148:151], v[186:189], v[30:33]
	v_mfma_f32_16x16x32_f16 v[26:29], v[162:165], v[186:189], v[26:29]
	v_mfma_f32_16x16x32_f16 v[12:15], v[148:151], v[194:197], v[12:15]
	v_mfma_f32_16x16x32_f16 v[8:11], v[162:165], v[194:197], v[8:11]
	s_setprio 0
	s_barrier
	v_add_u32_e32 v16, 0x10000, v159
	ds_read_b128 v[144:147], v16
	ds_read_b128 v[148:151], v16 offset:1024
	ds_read_b128 v[152:155], v16 offset:2048
	ds_read_b128 v[162:165], v16 offset:3072
	s_add_i32 s8, s8, s71
	v_lshl_add_u64 v[156:157], v[248:249], 0, s[90:91]
	s_mov_b32 m0, s8
	s_nop 0
	global_load_lds_dwordx4 v[156:157], off
	v_lshl_add_u64 v[156:157], v[250:251], 0, s[90:91]
	s_add_i32 m0, s8, 0x2000
	s_nop 0
	global_load_lds_dwordx4 v[156:157], off
	s_waitcnt vmcnt(6)
	s_barrier
	s_setprio 1
	v_mfma_f32_16x16x32_f16 v[54:57], v[198:201], v[166:169], v[54:57]
	v_mfma_f32_16x16x32_f16 v[50:53], v[234:237], v[166:169], v[50:53]
	v_mfma_f32_16x16x32_f16 v[38:41], v[198:201], v[174:177], v[38:41]
	v_mfma_f32_16x16x32_f16 v[34:37], v[234:237], v[174:177], v[34:37]
	v_mfma_f32_16x16x32_f16 v[22:25], v[198:201], v[182:185], v[22:25]
	v_mfma_f32_16x16x32_f16 v[18:21], v[234:237], v[182:185], v[18:21]
	v_mfma_f32_16x16x32_f16 v[4:7], v[198:201], v[190:193], v[4:7]
	v_mfma_f32_16x16x32_f16 v[0:3], v[234:237], v[190:193], v[0:3]
	v_mfma_f32_16x16x32_f16 v[54:57], v[230:233], v[170:173], v[54:57]
	v_mfma_f32_16x16x32_f16 v[50:53], v[238:241], v[170:173], v[50:53]
	v_mfma_f32_16x16x32_f16 v[38:41], v[230:233], v[178:181], v[38:41]
	v_mfma_f32_16x16x32_f16 v[34:37], v[238:241], v[178:181], v[34:37]
	v_mfma_f32_16x16x32_f16 v[22:25], v[230:233], v[186:189], v[22:25]
	v_mfma_f32_16x16x32_f16 v[18:21], v[238:241], v[186:189], v[18:21]
	v_mfma_f32_16x16x32_f16 v[4:7], v[230:233], v[194:197], v[4:7]
	v_mfma_f32_16x16x32_f16 v[0:3], v[238:241], v[194:197], v[0:3]
	s_setprio 0
	s_barrier
	s_add_u32 s6, s6, 0x100
	s_addc_u32 s7, s7, 0
	s_add_u32 s41, s41, 0x100
	s_addc_u32 vcc_lo, vcc_lo, 0
	s_cmp_ge_u32 vcc_hi, s77
	s_mov_b32 s8, vcc_hi
	s_cbranch_scc0 .LBB0_829
	s_waitcnt lgkmcnt(0)
	v_lshl_add_u32 v162, s36, 8, v139
	v_ashrrev_i32_e32 v16, 31, v162
	s_lshl_b32 s3, s3, 8
	v_mul_lo_u32 v163, s54, v16
	v_mul_lo_u32 v16, s55, v162
	v_mad_u64_u32 v[144:145], s[6:7], s54, v162, 0
	s_or_b32 s3, s3, s89
	v_add3_u32 v145, v145, v163, v16
	s_mov_b64 s[6:7], -1
	s_and_b64 vcc, exec, s[42:43]
	s_movk_i32 s86, 0x41ff
	s_cbranch_vccz .LBB0_864
	v_cndmask_b32_e64 v16, 0, 1, s[48:49]
	v_cmp_ne_u32_e64 s[40:41], 1, v16
	s_andn2_b64 vcc, exec, s[48:49]
	v_or_b32_e32 v16, s3, v158
	v_lshlrev_b32_e32 v16, 1, v16
	v_lshl_add_u64 v[146:147], s[52:53], 0, v[16:17]
	v_lshl_add_u64 v[148:149], v[144:145], 1, v[146:147]
	s_cbranch_vccnz .Lep0_0
	v_max_f32_e32 v150, 0, v126
	v_max_f32_e32 v151, 0, v127
	v_max_f32_e32 v152, 0, v128
	v_max_f32_e32 v153, 0, v129
	v_max_f32_e32 v154, 0, v122
	v_max_f32_e32 v155, 0, v123
	v_max_f32_e32 v156, 0, v124
	v_max_f32_e32 v157, 0, v125
	v_pk_mul_f32 v[150:151], v[150:151], v[150:151]
	v_pk_mul_f32 v[152:153], v[152:153], v[152:153]
	v_pk_mul_f32 v[154:155], v[154:155], v[154:155]
	v_pk_mul_f32 v[156:157], v[156:157], v[156:157]
	v_cvt_pk_f16_f32 v150, v150, v151
	v_cvt_pk_f16_f32 v151, v152, v153
	v_cvt_pk_f16_f32 v152, v154, v155
	v_cvt_pk_f16_f32 v153, v156, v157
	s_branch .Lep1_0
